# GLA step 2a: conditional running-total LDS writes deferred past the next d-tile's math (bpermute/write round trips overlapped)
# speedup vs baseline: 1.0309x; 1.0090x over previous
.LBB0_334:
	s_waitcnt vmcnt(6)
	v_perm_b32 v2, v70, v66, s33
	v_perm_b32 v66, v70, v66, s72
	ds_write2_b32 v168, v2, v66 offset1:32
	v_perm_b32 v2, v71, v67, s33
	ds_write_b32 v169, v2 offset:24576
	v_perm_b32 v2, v71, v67, s72
	ds_write_b32 v170, v2 offset:24576
	v_perm_b32 v2, v72, v68, s33
	ds_write_b32 v171, v2 offset:24576
	v_perm_b32 v2, v72, v68, s72
	ds_write_b32 v172, v2 offset:24576
	v_perm_b32 v2, v73, v69, s33
	ds_write_b32 v173, v2 offset:24576
	v_perm_b32 v2, v73, v69, s72
	ds_write_b32 v174, v2 offset:24576
	s_waitcnt vmcnt(5)
	v_perm_b32 v2, v62, v58, s33
	v_perm_b32 v58, v62, v58, s72
	ds_write2_b32 v175, v2, v58 offset1:32
	v_perm_b32 v2, v63, v59, s33
	ds_write_b32 v176, v2 offset:24576
	v_perm_b32 v2, v63, v59, s72
	ds_write_b32 v177, v2 offset:24576
	v_perm_b32 v2, v64, v60, s33
	ds_write_b32 v178, v2 offset:24576
	v_perm_b32 v2, v64, v60, s72
	ds_write_b32 v179, v2 offset:24576
	v_perm_b32 v2, v65, v61, s33
	ds_write_b32 v180, v2 offset:24576
	v_perm_b32 v2, v65, v61, s72
	s_and_b64 vcc, exec, s[4:5]
	v_mov_b64_e32 v[90:91], v[108:109]
	v_mov_b64_e32 v[96:97], v[108:109]
	v_mov_b64_e32 v[94:95], v[116:117]
	v_mov_b64_e32 v[92:93], v[118:119]
	v_mov_b32_e32 v211, v117
	v_mov_b32_e32 v215, v117
	v_mov_b32_e32 v219, v117
	v_mov_b32_e32 v210, v116
	v_mov_b32_e32 v135, v119
	v_mov_b32_e32 v209, v118
	v_mov_b32_e32 v214, v116
	v_mov_b32_e32 v212, v119
	v_mov_b32_e32 v213, v118
	v_mov_b32_e32 v218, v116
	v_mov_b32_e32 v216, v119
	v_mov_b32_e32 v217, v118
	ds_write_b32 v181, v2 offset:24576
	s_cbranch_vccnz .LBB0_303
	s_waitcnt vmcnt(4)
	v_cndmask_b32_e64 v57, 0, v57, s[10:11]
	v_cndmask_b32_e64 v56, 0, v56, s[10:11]
	v_cndmask_b32_e64 v55, 0, v55, s[10:11]
	v_cndmask_b32_e64 v54, 0, v54, s[10:11]
	s_nop 1
	v_mfma_f32_16x16x32_bf16 v[58:61], v[54:57], v[6:9], 0
	v_mfma_f32_16x16x32_bf16 v[62:65], v[54:57], v[10:13], 0
	s_nop 6
	v_add_f32_e32 v2, v111, v58
	v_min_f32_e32 v67, 0, v2
	v_mul_f32_e64 v2, |v2|, s73
	v_exp_f32_e32 v2, v2
	s_nop 0
	v_add_f32_e32 v2, 1.0, v2
	v_log_f32_e32 v2, v2
	s_nop 0
	v_mul_f32_e32 v58, 0x3f317217, v2
	v_fma_f32 v58, v2, s67, -v58
	v_fmac_f32_e32 v58, 0x3377d1cf, v2
	v_fmac_f32_e32 v58, 0x3f317217, v2
	v_mov_b32_e32 v2, v58
	v_mov_b32_e32 v58, 0
	v_sub_f32_e32 v69, v2, v58
	v_add_f32_e32 v2, v111, v59
	v_min_f32_e32 v58, 0, v2
	v_mul_f32_e64 v2, |v2|, s73
	v_exp_f32_e32 v2, v2
	s_nop 0
	v_add_f32_e32 v2, 1.0, v2
	v_log_f32_e32 v2, v2
	s_nop 0
	v_mul_f32_e32 v59, 0x3f317217, v2
	v_fma_f32 v59, v2, s67, -v59
	v_fmac_f32_e32 v59, 0x3377d1cf, v2
	v_fmac_f32_e32 v59, 0x3f317217, v2
	v_mov_b32_e32 v2, v59
	v_mov_b32_e32 v59, 0
	v_sub_f32_e32 v2, v2, v59
	v_sub_f32_e32 v70, v58, v2
	v_add_f32_e32 v2, v111, v60
	v_min_f32_e32 v58, 0, v2
	v_mul_f32_e64 v2, |v2|, s73
	v_exp_f32_e32 v2, v2
	s_nop 0
	v_add_f32_e32 v2, 1.0, v2
	v_log_f32_e32 v2, v2
	s_nop 0
	v_mul_f32_e32 v59, 0x3f317217, v2
	v_fma_f32 v59, v2, s67, -v59
	v_fmac_f32_e32 v59, 0x3377d1cf, v2
	v_fmac_f32_e32 v59, 0x3f317217, v2
	v_mov_b32_e32 v2, v59
	v_mov_b32_e32 v59, 0
	v_sub_f32_e32 v2, v2, v59
	v_sub_f32_e32 v71, v58, v2
	v_add_f32_e32 v2, v111, v61
	v_min_f32_e32 v58, 0, v2
	v_mul_f32_e64 v2, |v2|, s73
	v_exp_f32_e32 v2, v2
	s_nop 0
	v_add_f32_e32 v2, 1.0, v2
	v_log_f32_e32 v2, v2
	s_nop 0
	v_mul_f32_e32 v59, 0x3f317217, v2
	v_fma_f32 v59, v2, s67, -v59
	v_fmac_f32_e32 v59, 0x3377d1cf, v2
	v_fmac_f32_e32 v59, 0x3f317217, v2
	v_mov_b32_e32 v2, v59
	v_mov_b32_e32 v59, 0
	v_sub_f32_e32 v2, v2, v59
	v_sub_f32_e32 v72, v58, v2
	v_add_f32_e32 v2, v139, v62
	v_min_f32_e32 v66, 0, v2
	v_mul_f32_e64 v2, |v2|, s73
	v_exp_f32_e32 v2, v2
	v_and_b32_e32 v62, 64, v1
	v_add_f32_e32 v2, 1.0, v2
	v_log_f32_e32 v2, v2
	s_nop 0
	v_mul_f32_e32 v58, 0x3f317217, v2
	v_fma_f32 v58, v2, s67, -v58
	v_fmac_f32_e32 v58, 0x3377d1cf, v2
	v_fmac_f32_e32 v58, 0x3f317217, v2
	v_mov_b32_e32 v2, v58
	v_mov_b32_e32 v58, 0
	v_sub_f32_e32 v68, v2, v58
	v_add_u32_e32 v2, -16, v1
	v_pk_add_f32 v[58:59], v[66:67], v[68:69] neg_lo:[0,1] neg_hi:[0,1]
	v_cmp_lt_i32_e32 vcc, v2, v62
	v_subrev_u32_e32 v66, 32, v1
	v_pk_mul_f32 v[90:91], v[58:59], s[96:97] op_sel_hi:[1,0]
	v_cndmask_b32_e32 v2, v2, v1, vcc
	v_cmp_lt_i32_e32 vcc, v66, v62
	v_fmamk_f32 v94, v70, 0x3d800000, v91
	v_fmamk_f32 v93, v71, 0x3d800000, v94
	v_cndmask_b32_e32 v66, v66, v1, vcc
	v_lshlrev_b32_e32 v67, 2, v66
	v_subrev_u32_e32 v66, 48, v1
	v_cmp_lt_i32_e32 vcc, v66, v62
	v_lshlrev_b32_e32 v2, 2, v2
	v_or_b32_e32 v62, v62, v166
	v_cndmask_b32_e32 v66, v66, v1, vcc
	v_fmamk_f32 v92, v72, 0x3d800000, v93
	v_lshlrev_b32_e32 v68, 2, v66
	v_lshlrev_b32_e32 v66, 2, v62
	ds_bpermute_b32 v62, v2, v92
	ds_bpermute_b32 v69, v67, v92
	ds_bpermute_b32 v70, v68, v92
	v_mfma_f32_16x16x32_bf16 v[58:61], v[54:57], v[14:17], 0
	s_waitcnt lgkmcnt(2)
	v_cndmask_b32_e64 v62, v62, 0, s[6:7]
	s_waitcnt lgkmcnt(1)
	v_cndmask_b32_e64 v69, 0, v69, s[12:13]
	v_add_f32_e32 v62, v62, v69
	s_waitcnt lgkmcnt(0)
	v_cndmask_b32_e64 v69, 0, v70, s[8:9]
	v_add_f32_e32 v95, v62, v69
	v_add_f32_e32 v62, v95, v92
	ds_bpermute_b32 v220, v66, v62
	v_mfma_f32_16x16x32_bf16 v[54:57], v[54:57], v[18:21], 0
	v_add_f32_e32 v62, v139, v63
	v_min_f32_e32 v63, 0, v62
	v_mul_f32_e64 v62, |v62|, s73
	v_exp_f32_e32 v62, v62
	s_nop 0
	v_add_f32_e32 v62, 1.0, v62
	v_log_f32_e32 v62, v62
	s_nop 0
	v_mul_f32_e32 v69, 0x3f317217, v62
	v_fma_f32 v69, v62, s67, -v69
	v_fmac_f32_e32 v69, 0x3377d1cf, v62
	v_fmac_f32_e32 v69, 0x3f317217, v62
	v_mov_b32_e32 v62, v69
	v_mov_b32_e32 v69, 0
	v_sub_f32_e32 v62, v62, v69
	v_sub_f32_e32 v62, v63, v62
	v_add_f32_e32 v63, v139, v64
	v_min_f32_e32 v64, 0, v63
	v_mul_f32_e64 v63, |v63|, s73
	v_exp_f32_e32 v63, v63
	v_fmamk_f32 v210, v62, 0x3d800000, v90
	v_add_f32_e32 v63, 1.0, v63
	v_log_f32_e32 v63, v63
	s_nop 0
	v_mul_f32_e32 v69, 0x3f317217, v63
	v_fma_f32 v69, v63, s67, -v69
	v_fmac_f32_e32 v69, 0x3377d1cf, v63
	v_fmac_f32_e32 v69, 0x3f317217, v63
	v_mov_b32_e32 v63, v69
	v_mov_b32_e32 v69, 0
	v_sub_f32_e32 v63, v63, v69
	v_sub_f32_e32 v63, v64, v63
	v_add_f32_e32 v64, v139, v65
	v_min_f32_e32 v65, 0, v64
	v_mul_f32_e64 v64, |v64|, s73
	v_exp_f32_e32 v64, v64
	v_fmamk_f32 v135, v63, 0x3d800000, v210
	v_add_f32_e32 v64, 1.0, v64
	v_log_f32_e32 v64, v64
	s_nop 0
	v_mul_f32_e32 v69, 0x3f317217, v64
	v_fma_f32 v69, v64, s67, -v69
	v_fmac_f32_e32 v69, 0x3377d1cf, v64
	v_fmac_f32_e32 v69, 0x3f317217, v64
	v_mov_b32_e32 v64, v69
	v_mov_b32_e32 v69, 0
	v_sub_f32_e32 v64, v64, v69
	v_sub_f32_e32 v64, v65, v64
	v_fmamk_f32 v209, v64, 0x3d800000, v135
	s_and_saveexec_b64 s[0:1], s[6:7]
	s_cbranch_execz .Ldw_0
	s_waitcnt lgkmcnt(0)
	ds_write_b32 v167, v220
.Ldw_0:
	s_or_b64 exec, exec, s[0:1]
	ds_bpermute_b32 v62, v2, v209
	ds_bpermute_b32 v63, v67, v209
	ds_bpermute_b32 v64, v68, v209
	s_waitcnt lgkmcnt(2)
	v_cndmask_b32_e64 v62, v62, 0, s[6:7]
	s_waitcnt lgkmcnt(1)
	v_cndmask_b32_e64 v63, 0, v63, s[12:13]
	v_add_f32_e32 v62, v62, v63
	s_waitcnt lgkmcnt(0)
	v_cndmask_b32_e64 v63, 0, v64, s[8:9]
	v_add_f32_e32 v211, v62, v63
	v_add_f32_e32 v62, v209, v211
	ds_bpermute_b32 v221, v66, v62
	v_add_f32_e32 v58, v140, v58
	v_min_f32_e32 v63, 0, v58
	v_mul_f32_e64 v58, |v58|, s73
	v_exp_f32_e32 v58, v58
	v_add_f32_e32 v54, v141, v54
	v_add_f32_e32 v58, 1.0, v58
	s_nop 0
	v_log_f32_e32 v58, v58
	s_nop 0
	v_mul_f32_e32 v62, 0x3f317217, v58
	v_fma_f32 v62, v58, s67, -v62
	v_fmac_f32_e32 v62, 0x3377d1cf, v58
	v_fmac_f32_e32 v62, 0x3f317217, v58
	v_mov_b32_e32 v58, v62
	v_mov_b32_e32 v62, 0
	v_sub_f32_e32 v65, v58, v62
	v_add_f32_e32 v58, v140, v59
	v_min_f32_e32 v59, 0, v58
	v_mul_f32_e64 v58, |v58|, s73
	v_exp_f32_e32 v58, v58
	s_nop 0
	v_add_f32_e32 v58, 1.0, v58
	v_log_f32_e32 v58, v58
	s_nop 0
	v_mul_f32_e32 v62, 0x3f317217, v58
	v_fma_f32 v62, v58, s67, -v62
	v_fmac_f32_e32 v62, 0x3377d1cf, v58
	v_fmac_f32_e32 v62, 0x3f317217, v58
	v_mov_b32_e32 v58, v62
	v_mov_b32_e32 v62, 0
	v_sub_f32_e32 v58, v58, v62
	v_sub_f32_e32 v69, v59, v58
	v_add_f32_e32 v58, v140, v60
	v_min_f32_e32 v59, 0, v58
	v_mul_f32_e64 v58, |v58|, s73
	v_exp_f32_e32 v58, v58
	v_min_f32_e32 v62, 0, v54
	v_mul_f32_e64 v54, |v54|, s73
	v_exp_f32_e32 v54, v54
	v_add_f32_e32 v58, 1.0, v58
	v_add_f32_e32 v54, 1.0, v54
	s_nop 0
	v_log_f32_e32 v58, v58
	s_nop 0
	v_mul_f32_e32 v60, 0x3f317217, v58
	v_fma_f32 v60, v58, s67, -v60
	v_fmac_f32_e32 v60, 0x3377d1cf, v58
	v_fmac_f32_e32 v60, 0x3f317217, v58
	v_mov_b32_e32 v58, v60
	v_mov_b32_e32 v60, 0
	v_sub_f32_e32 v58, v58, v60
	v_sub_f32_e32 v60, v59, v58
	v_add_f32_e32 v58, v140, v61
	v_min_f32_e32 v59, 0, v58
	v_mul_f32_e64 v58, |v58|, s73
	v_exp_f32_e32 v58, v58
	s_nop 0
	v_add_f32_e32 v58, 1.0, v58
	v_log_f32_e32 v58, v58
	s_nop 0
	v_mul_f32_e32 v61, 0x3f317217, v58
	v_fma_f32 v61, v58, s67, -v61
	v_fmac_f32_e32 v61, 0x3377d1cf, v58
	v_fmac_f32_e32 v61, 0x3f317217, v58
	v_mov_b32_e32 v58, v61
	v_mov_b32_e32 v61, 0
	v_sub_f32_e32 v58, v58, v61
	v_sub_f32_e32 v61, v59, v58
	s_nop 0
	v_log_f32_e32 v54, v54
	s_nop 0
	v_mul_f32_e32 v58, 0x3f317217, v54
	v_fma_f32 v58, v54, s67, -v58
	v_fmac_f32_e32 v58, 0x3377d1cf, v54
	v_fmac_f32_e32 v58, 0x3f317217, v54
	v_mov_b32_e32 v54, v58
	v_mov_b32_e32 v58, 0
	v_sub_f32_e32 v64, v54, v58
	v_pk_add_f32 v[58:59], v[62:63], v[64:65] neg_lo:[0,1] neg_hi:[0,1]
	s_nop 0
	v_pk_mul_f32 v[96:97], v[58:59], s[96:97] op_sel_hi:[1,0]
	s_nop 0
	v_fmamk_f32 v214, v69, 0x3d800000, v97
	v_fmamk_f32 v212, v60, 0x3d800000, v214
	v_fmamk_f32 v213, v61, 0x3d800000, v212
	s_and_saveexec_b64 s[0:1], s[6:7]
	s_cbranch_execz .Ldw_1
	s_waitcnt lgkmcnt(0)
	ds_write_b32 v167, v221 offset:64
.Ldw_1:
	s_or_b64 exec, exec, s[0:1]
	ds_bpermute_b32 v54, v2, v213
	ds_bpermute_b32 v58, v67, v213
	ds_bpermute_b32 v59, v68, v213
	s_waitcnt lgkmcnt(2)
	v_cndmask_b32_e64 v54, v54, 0, s[6:7]
	s_waitcnt lgkmcnt(1)
	v_cndmask_b32_e64 v58, 0, v58, s[12:13]
	v_add_f32_e32 v54, v54, v58
	s_waitcnt lgkmcnt(0)
	v_cndmask_b32_e64 v58, 0, v59, s[8:9]
	v_add_f32_e32 v215, v54, v58
	v_add_f32_e32 v54, v213, v215
	ds_bpermute_b32 v222, v66, v54
	v_add_f32_e32 v54, v141, v55
	v_min_f32_e32 v55, 0, v54
	v_mul_f32_e64 v54, |v54|, s73
	v_exp_f32_e32 v54, v54
	s_nop 0
	v_add_f32_e32 v54, 1.0, v54
	v_log_f32_e32 v54, v54
	s_nop 0
	v_mul_f32_e32 v58, 0x3f317217, v54
	v_fma_f32 v58, v54, s67, -v58
	v_fmac_f32_e32 v58, 0x3377d1cf, v54
	v_fmac_f32_e32 v58, 0x3f317217, v54
	v_mov_b32_e32 v54, v58
	v_mov_b32_e32 v58, 0
	v_sub_f32_e32 v54, v54, v58
	v_sub_f32_e32 v54, v55, v54
	v_add_f32_e32 v55, v141, v56
	v_min_f32_e32 v56, 0, v55
	v_mul_f32_e64 v55, |v55|, s73
	v_exp_f32_e32 v55, v55
	v_fmamk_f32 v218, v54, 0x3d800000, v96
	v_add_f32_e32 v55, 1.0, v55
	v_log_f32_e32 v55, v55
	s_nop 0
	v_mul_f32_e32 v58, 0x3f317217, v55
	v_fma_f32 v58, v55, s67, -v58
	v_fmac_f32_e32 v58, 0x3377d1cf, v55
	v_fmac_f32_e32 v58, 0x3f317217, v55
	v_mov_b32_e32 v55, v58
	v_mov_b32_e32 v58, 0
	v_sub_f32_e32 v55, v55, v58
	v_sub_f32_e32 v55, v56, v55
	v_add_f32_e32 v56, v141, v57
	v_min_f32_e32 v57, 0, v56
	v_mul_f32_e64 v56, |v56|, s73
	v_exp_f32_e32 v56, v56
	v_fmamk_f32 v216, v55, 0x3d800000, v218
	v_add_f32_e32 v56, 1.0, v56
	v_log_f32_e32 v56, v56
	s_nop 0
	v_mul_f32_e32 v58, 0x3f317217, v56
	v_fma_f32 v58, v56, s67, -v58
	v_fmac_f32_e32 v58, 0x3377d1cf, v56
	v_fmac_f32_e32 v58, 0x3f317217, v56
	v_mov_b32_e32 v56, v58
	v_mov_b32_e32 v58, 0
	v_sub_f32_e32 v56, v56, v58
	v_sub_f32_e32 v56, v57, v56
	v_fmamk_f32 v217, v56, 0x3d800000, v216
	s_and_saveexec_b64 s[0:1], s[6:7]
	s_cbranch_execz .Ldw_2
	s_waitcnt lgkmcnt(0)
	ds_write_b32 v167, v222 offset:128
.Ldw_2:
	s_or_b64 exec, exec, s[0:1]
	ds_bpermute_b32 v2, v2, v217
	ds_bpermute_b32 v54, v67, v217
	ds_bpermute_b32 v55, v68, v217
	s_waitcnt lgkmcnt(2)
	v_cndmask_b32_e64 v2, v2, 0, s[6:7]
	s_waitcnt lgkmcnt(1)
	v_cndmask_b32_e64 v54, 0, v54, s[12:13]
	v_add_f32_e32 v2, v2, v54
	s_waitcnt lgkmcnt(0)
	v_cndmask_b32_e64 v54, 0, v55, s[8:9]
	v_add_f32_e32 v219, v2, v54
	v_add_f32_e32 v2, v217, v219
	ds_bpermute_b32 v2, v66, v2
	s_and_saveexec_b64 s[0:1], s[6:7]
	s_cbranch_execz .LBB0_302
	s_waitcnt lgkmcnt(0)
	ds_write_b32 v167, v2 offset:192
	s_branch .LBB0_302
